# MoBA iteration: first two MFMA gaps after the barrier left bare (displaced exps moved to the tail), on top of the no-flip GEMM
# speedup vs baseline: 1.0013x; 1.0013x over previous
; #define ATT_MFMA(a, b, c) __builtin_amdgcn_mfma_f32_32x32x16_bf16((a), (b), (c), 0, 0, 0)
; #define ATT_RDTR(dst, addr, off) asm volatile("ds_read_b64_tr_b16 %0, %1 offset:%c2" : "=&v"(dst) : "v"(addr), "i"(off) : "memory")
; template <bool DO_QK, bool DO_PV> __device__ __forceinline__ void mseg(f32x16& p0, f32x16& p1, f32x16* o, unsigned kaddr, unsigned vaddr, const bf16x8* qr, const f32x16& cin,
;                                                                      bf16x8 pa0, bf16x8 pa1, bf16x8 pa2, bf16x8 pa3) {
;     ...
;     if (DO_PV) {
;         if (!DO_QK) asm volatile("s_waitcnt lgkmcnt(0)" : "+v"(vl[0]), "+v"(vh[0]), "+v"(vl[1]), "+v"(vh[1]), "+v"(vl[2]), "+v"(vh[2]), "+v"(vl[3]), "+v"(vh[3]) :: "memory");
;         __builtin_amdgcn_sched_barrier(0);
;     ...
;         o[0] = ATT_MFMA(pa0, ATT_PK2(vl[0], vh[0]), o[0]); o[0] = ATT_MFMA(pa1, ATT_PK2(vl[1], vh[1]), o[0]);
;         o[0] = ATT_MFMA(pa2, ATT_PK2(vl[2], vh[2]), o[0]); o[0] = ATT_MFMA(pa3, ATT_PK2(vl[3], vh[3]), o[0]);
;         __builtin_amdgcn_sched_barrier(0);
;         ATT_RDTR(vl[0], vaddr, 4096); ATT_RDTR(vh[0], vaddr, 4608); ATT_RDTR(vl[1], vaddr, 5120); ATT_RDTR(vh[1], vaddr, 5632);
;         ATT_RDTR(vl[2], vaddr, 6144); ATT_RDTR(vh[2], vaddr, 6656); ATT_RDTR(vl[3], vaddr, 7168); ATT_RDTR(vh[3], vaddr, 7680);
;         asm volatile("s_waitcnt lgkmcnt(0)" : "+v"(vl[0]), "+v"(vh[0]), "+v"(vl[1]), "+v"(vh[1]), "+v"(vl[2]), "+v"(vh[2]), "+v"(vl[3]), "+v"(vh[3]) :: "memory");
;         __builtin_amdgcn_sched_barrier(0);
;         o[1] = ATT_MFMA(pa0, ATT_PK2(vl[0], vh[0]), o[1]); o[1] = ATT_MFMA(pa1, ATT_PK2(vl[1], vh[1]), o[1]);
;         o[1] = ATT_MFMA(pa2, ATT_PK2(vl[2], vh[2]), o[1]); o[1] = ATT_MFMA(pa3, ATT_PK2(vl[3], vh[3]), o[1]);
.Lmb1_skVA:
.Lmb1_A_g1top:
	s_add_i32 s42, s44, 0x2000
	s_add_i32 s98, s44, 0x4000
	s_and_b32 s45, s98, 0x6000
	v_add_u32_e32 v133, s45, v130
	ds_read_b128 v[154:157], v133
	ds_read_b128 v[158:161], v133 offset:512
	ds_read_b128 v[162:165], v133 offset:2048
	ds_read_b128 v[166:169], v133 offset:2560
	ds_read_b128 v[170:173], v133 offset:4096
	ds_read_b128 v[174:177], v133 offset:4608
	ds_read_b128 v[178:181], v133 offset:6144
	ds_read_b128 v[182:185], v133 offset:6656
	s_and_b32 s45, s42, 0x6000
	v_add_u32_e32 v218, s45, v132
	s_add_i32 s98, s34, 2
	s_cmp_ge_i32 s34, s31
	s_cbranch_scc1 .Lmb1_A_near
	v_mfma_f32_32x32x16_bf16 v[16:31], v[108:111], v[186:189], v[16:31]
	v_mfma_f32_32x32x16_bf16 v[16:31], v[104:107], v[190:193], v[16:31]
	v_mfma_f32_32x32x16_bf16 v[16:31], v[100:103], v[194:197], v[16:31]
	v_exp_f32_e32 v64, v64
	v_exp_f32_e32 v48, v48
	v_mfma_f32_32x32x16_bf16 v[16:31], v[96:99], v[198:201], v[16:31]
	v_exp_f32_e32 v65, v65
	v_exp_f32_e32 v49, v49
	v_add_f32_e32 v252, v64, v48
	v_mfma_f32_32x32x16_bf16 v[32:47], v[108:111], v[202:205], v[32:47]
	v_exp_f32_e32 v66, v66
	v_exp_f32_e32 v50, v50
	v_add_f32_e32 v253, v65, v49
	v_add_f32_e32 v252, v252, v253
	ds_read_b64_tr_b16 v[186:187], v218
	ds_read_b64_tr_b16 v[188:189], v218 offset:512
	v_mfma_f32_32x32x16_bf16 v[32:47], v[104:107], v[206:209], v[32:47]
	v_exp_f32_e32 v67, v67
	v_exp_f32_e32 v51, v51
	v_add_f32_e32 v253, v66, v50
	v_add_f32_e32 v252, v252, v253
	ds_read_b64_tr_b16 v[190:191], v218 offset:1024
	ds_read_b64_tr_b16 v[192:193], v218 offset:1536
	v_mfma_f32_32x32x16_bf16 v[32:47], v[100:103], v[210:213], v[32:47]
	v_exp_f32_e32 v68, v68
	v_exp_f32_e32 v52, v52
	v_add_f32_e32 v253, v67, v51
	v_add_f32_e32 v252, v252, v253
	ds_read_b64_tr_b16 v[194:195], v218 offset:2048
	ds_read_b64_tr_b16 v[196:197], v218 offset:2560
	v_mfma_f32_32x32x16_bf16 v[32:47], v[96:99], v[214:217], v[32:47]
	v_exp_f32_e32 v69, v69
	v_exp_f32_e32 v53, v53
	v_add_f32_e32 v253, v68, v52
	v_add_f32_e32 v252, v252, v253
	ds_read_b64_tr_b16 v[198:199], v218 offset:3072
	ds_read_b64_tr_b16 v[200:201], v218 offset:3584
	s_and_b64 vcc, exec, s[6:7]
	s_cbranch_vccnz .Lmb1_A_g0mid
	s_add_i32 s45, s37, 1
	s_cmp_ge_u32 s45, s30
	s_cbranch_scc1 .Lmb1_skKAm
	s_add_i32 s45, s44, 0x2000
	s_and_b32 s45, s45, 0x6000
	s_add_i32 s45, s45, s74
	s_mov_b32 s99, m0
	s_mov_b32 m0, s45
	s_nop 0
	global_load_lds_dwordx4 v[114:115], off
	s_mov_b32 m0, s99
	s_mov_b32 s43, 1

; template <bool DO_QK, bool DO_PV> __device__ __forceinline__ void mseg(f32x16& p0, f32x16& p1, f32x16* o, unsigned kaddr, unsigned vaddr, const bf16x8* qr, const f32x16& cin,
;                                                                      bf16x8 pa0, bf16x8 pa1, bf16x8 pa2, bf16x8 pa3) {
;     ...
;     if (DO_QK) {
;         if (DO_PV) asm volatile("s_waitcnt lgkmcnt(8)" : "+v"(kf[0]), "+v"(kf[1]), "+v"(kf[2]), "+v"(kf[3]) :: "memory");
;         else asm volatile("s_waitcnt lgkmcnt(0)" : "+v"(kf[0]), "+v"(kf[1]), "+v"(kf[2]), "+v"(kf[3]) :: "memory");
;         __builtin_amdgcn_sched_barrier(0);
;         p0 = ATT_MFMA(kf[0], qr[0], cin); p1 = ATT_MFMA(kf[1], qr[0], cin);
;         p0 = ATT_MFMA(kf[2], qr[1], p0);  p1 = ATT_MFMA(kf[3], qr[1], p1);
;         __builtin_amdgcn_sched_barrier(0);
;         ATT_RD128(kf[0], kaddr, 4096); ATT_RD128(kf[1], kaddr, 4608); ATT_RD128(kf[2], kaddr, 6144); ATT_RD128(kf[3], kaddr, 6656);
;         asm volatile("s_waitcnt lgkmcnt(0)" : "+v"(kf[0]), "+v"(kf[1]), "+v"(kf[2]), "+v"(kf[3]), "+v"(vl[0]), "+v"(vh[0]), "+v"(vl[1]), "+v"(vh[1]), "+v"(vl[2]), "+v"(vh[2]), "+v"(vl[3]), "+v"(vh[3]) :: "memory");
;         __builtin_amdgcn_sched_barrier(0);
;         p0 = ATT_MFMA(kf[0], qr[2], p0);  p1 = ATT_MFMA(kf[1], qr[2], p1);
;         p0 = ATT_MFMA(kf[2], qr[3], p0);  p1 = ATT_MFMA(kf[3], qr[3], p1);
;         __builtin_amdgcn_sched_barrier(0);
;     }
;     if (DO_PV) {
;         if (!DO_QK) asm volatile("s_waitcnt lgkmcnt(0)" : "+v"(vl[0]), "+v"(vh[0]), "+v"(vl[1]), "+v"(vh[1]), "+v"(vl[2]), "+v"(vh[2]), "+v"(vl[3]), "+v"(vh[3]) :: "memory");
;         __builtin_amdgcn_sched_barrier(0);
;     ...
;         o[0] = ATT_MFMA(pa0, ATT_PK2(vl[0], vh[0]), o[0]); o[0] = ATT_MFMA(pa1, ATT_PK2(vl[1], vh[1]), o[0]);
;         o[0] = ATT_MFMA(pa2, ATT_PK2(vl[2], vh[2]), o[0]); o[0] = ATT_MFMA(pa3, ATT_PK2(vl[3], vh[3]), o[0]);
;         __builtin_amdgcn_sched_barrier(0);
;         ATT_RDTR(vl[0], vaddr, 4096); ATT_RDTR(vh[0], vaddr, 4608); ATT_RDTR(vl[1], vaddr, 5120); ATT_RDTR(vh[1], vaddr, 5632);
;         ATT_RDTR(vl[2], vaddr, 6144); ATT_RDTR(vh[2], vaddr, 6656); ATT_RDTR(vl[3], vaddr, 7168); ATT_RDTR(vh[3], vaddr, 7680);
;         asm volatile("s_waitcnt lgkmcnt(0)" : "+v"(vl[0]), "+v"(vh[0]), "+v"(vl[1]), "+v"(vh[1]), "+v"(vl[2]), "+v"(vh[2]), "+v"(vl[3]), "+v"(vh[3]) :: "memory");
;         __builtin_amdgcn_sched_barrier(0);
.Lmb1_skVAm:
.Lmb1_A_g0mid:
	s_waitcnt lgkmcnt(8)
	v_mfma_f32_32x32x16_bf16 v[236:251], v[154:157], v[92:95], v[220:235]
	v_exp_f32_e32 v70, v70
	v_exp_f32_e32 v54, v54
	v_add_f32_e32 v253, v69, v53
	v_add_f32_e32 v252, v252, v253
	v_cvt_pk_bf16_f32 v108, v64, v65
	v_cvt_pk_bf16_f32 v100, v48, v49
	ds_read_b64_tr_b16 v[202:203], v218 offset:4096
	ds_read_b64_tr_b16 v[204:205], v218 offset:4608
	v_mfma_f32_32x32x16_bf16 v[134:149], v[158:161], v[92:95], v[220:235]
	v_exp_f32_e32 v71, v71
	v_exp_f32_e32 v55, v55
	v_add_f32_e32 v253, v70, v54
	v_add_f32_e32 v252, v252, v253
	v_cvt_pk_bf16_f32 v109, v66, v67
	v_cvt_pk_bf16_f32 v101, v50, v51
	ds_read_b64_tr_b16 v[206:207], v218 offset:5120
	ds_read_b64_tr_b16 v[208:209], v218 offset:5632
	v_mfma_f32_32x32x16_bf16 v[236:251], v[162:165], v[88:91], v[236:251]
	v_exp_f32_e32 v72, v72
	v_exp_f32_e32 v56, v56
	v_add_f32_e32 v253, v71, v55
	v_add_f32_e32 v252, v252, v253
	v_cvt_pk_bf16_f32 v110, v68, v69
	v_cvt_pk_bf16_f32 v102, v52, v53
	ds_read_b64_tr_b16 v[210:211], v218 offset:6144
	ds_read_b64_tr_b16 v[212:213], v218 offset:6656
	v_mfma_f32_32x32x16_bf16 v[134:149], v[166:169], v[88:91], v[134:149]
	v_exp_f32_e32 v73, v73
	v_exp_f32_e32 v57, v57
	v_add_f32_e32 v253, v72, v56
	v_add_f32_e32 v252, v252, v253
	v_cvt_pk_bf16_f32 v111, v70, v71
	v_cvt_pk_bf16_f32 v103, v54, v55
	ds_read_b64_tr_b16 v[214:215], v218 offset:7168
	ds_read_b64_tr_b16 v[216:217], v218 offset:7680
	v_mfma_f32_32x32x16_bf16 v[236:251], v[170:173], v[84:87], v[236:251]
	v_exp_f32_e32 v74, v74
	v_exp_f32_e32 v58, v58
	v_add_f32_e32 v253, v73, v57
	v_add_f32_e32 v252, v252, v253
	v_cvt_pk_bf16_f32 v104, v72, v73
	v_cvt_pk_bf16_f32 v96, v56, v57
	v_mfma_f32_32x32x16_bf16 v[134:149], v[174:177], v[84:87], v[134:149]
	v_exp_f32_e32 v75, v75
	v_exp_f32_e32 v59, v59
	v_add_f32_e32 v253, v74, v58
	v_add_f32_e32 v252, v252, v253
	v_mfma_f32_32x32x16_bf16 v[236:251], v[178:181], v[80:83], v[236:251]
	v_exp_f32_e32 v76, v76
	v_exp_f32_e32 v60, v60
	v_add_f32_e32 v253, v75, v59
	v_add_f32_e32 v252, v252, v253
	v_cvt_pk_bf16_f32 v105, v74, v75
	v_cvt_pk_bf16_f32 v97, v58, v59
	v_mfma_f32_32x32x16_bf16 v[134:149], v[182:185], v[80:83], v[134:149]
	v_exp_f32_e32 v77, v77
	v_exp_f32_e32 v61, v61
	v_add_f32_e32 v253, v76, v60
	v_add_f32_e32 v252, v252, v253
	v_add_f32_e32 v253, v77, v61
	v_add_f32_e32 v252, v252, v253
	v_exp_f32_e32 v78, v78
	v_exp_f32_e32 v62, v62
	v_exp_f32_e32 v79, v79
	v_exp_f32_e32 v63, v63
	s_nop 0
	v_add_f32_e32 v253, v78, v62
	v_add_f32_e32 v252, v252, v253
	v_add_f32_e32 v253, v79, v63
	v_add_f32_e32 v252, v252, v253
	v_cvt_pk_bf16_f32 v106, v76, v77
	v_cvt_pk_bf16_f32 v98, v60, v61
	v_cvt_pk_bf16_f32 v107, v78, v79
	v_cvt_pk_bf16_f32 v99, v62, v63
	v_add_f32_e32 v131, v131, v252

; #define ATT_MFMA(a, b, c) __builtin_amdgcn_mfma_f32_32x32x16_bf16((a), (b), (c), 0, 0, 0)
; #define ATT_RDTR(dst, addr, off) asm volatile("ds_read_b64_tr_b16 %0, %1 offset:%c2" : "=&v"(dst) : "v"(addr), "i"(off) : "memory")
; template <bool DO_QK, bool DO_PV> __device__ __forceinline__ void mseg(f32x16& p0, f32x16& p1, f32x16* o, unsigned kaddr, unsigned vaddr, const bf16x8* qr, const f32x16& cin,
;                                                                      bf16x8 pa0, bf16x8 pa1, bf16x8 pa2, bf16x8 pa3) {
;     ...
;     if (DO_PV) {
;         if (!DO_QK) asm volatile("s_waitcnt lgkmcnt(0)" : "+v"(vl[0]), "+v"(vh[0]), "+v"(vl[1]), "+v"(vh[1]), "+v"(vl[2]), "+v"(vh[2]), "+v"(vl[3]), "+v"(vh[3]) :: "memory");
;         __builtin_amdgcn_sched_barrier(0);
;     ...
;         o[0] = ATT_MFMA(pa0, ATT_PK2(vl[0], vh[0]), o[0]); o[0] = ATT_MFMA(pa1, ATT_PK2(vl[1], vh[1]), o[0]);
;         o[0] = ATT_MFMA(pa2, ATT_PK2(vl[2], vh[2]), o[0]); o[0] = ATT_MFMA(pa3, ATT_PK2(vl[3], vh[3]), o[0]);
;         __builtin_amdgcn_sched_barrier(0);
;         ATT_RDTR(vl[0], vaddr, 4096); ATT_RDTR(vh[0], vaddr, 4608); ATT_RDTR(vl[1], vaddr, 5120); ATT_RDTR(vh[1], vaddr, 5632);
;         ATT_RDTR(vl[2], vaddr, 6144); ATT_RDTR(vh[2], vaddr, 6656); ATT_RDTR(vl[3], vaddr, 7168); ATT_RDTR(vh[3], vaddr, 7680);
;         asm volatile("s_waitcnt lgkmcnt(0)" : "+v"(vl[0]), "+v"(vh[0]), "+v"(vl[1]), "+v"(vh[1]), "+v"(vl[2]), "+v"(vh[2]), "+v"(vl[3]), "+v"(vh[3]) :: "memory");
;         __builtin_amdgcn_sched_barrier(0);
;         o[1] = ATT_MFMA(pa0, ATT_PK2(vl[0], vh[0]), o[1]); o[1] = ATT_MFMA(pa1, ATT_PK2(vl[1], vh[1]), o[1]);
;         o[1] = ATT_MFMA(pa2, ATT_PK2(vl[2], vh[2]), o[1]); o[1] = ATT_MFMA(pa3, ATT_PK2(vl[3], vh[3]), o[1]);
.Lmb1_skVB:
.Lmb1_B_g1top:
	s_add_i32 s42, s44, 0x2000
	s_add_i32 s98, s44, 0x4000
	s_and_b32 s45, s98, 0x6000
	v_add_u32_e32 v133, s45, v130
	ds_read_b128 v[154:157], v133
	ds_read_b128 v[158:161], v133 offset:512
	ds_read_b128 v[162:165], v133 offset:2048
	ds_read_b128 v[166:169], v133 offset:2560
	ds_read_b128 v[170:173], v133 offset:4096
	ds_read_b128 v[174:177], v133 offset:4608
	ds_read_b128 v[178:181], v133 offset:6144
	ds_read_b128 v[182:185], v133 offset:6656
	s_and_b32 s45, s42, 0x6000
	v_add_u32_e32 v218, s45, v132
	s_add_i32 s98, s34, 2
	s_cmp_ge_i32 s34, s31
	s_cbranch_scc1 .Lmb1_B_near
	v_mfma_f32_32x32x16_bf16 v[16:31], v[108:111], v[186:189], v[16:31]
	v_mfma_f32_32x32x16_bf16 v[16:31], v[104:107], v[190:193], v[16:31]
	v_mfma_f32_32x32x16_bf16 v[16:31], v[100:103], v[194:197], v[16:31]
	v_exp_f32_e32 v236, v236
	v_exp_f32_e32 v134, v134
	v_mfma_f32_32x32x16_bf16 v[16:31], v[96:99], v[198:201], v[16:31]
	v_exp_f32_e32 v237, v237
	v_exp_f32_e32 v135, v135
	v_add_f32_e32 v252, v236, v134
	v_mfma_f32_32x32x16_bf16 v[32:47], v[108:111], v[202:205], v[32:47]
	v_exp_f32_e32 v238, v238
	v_exp_f32_e32 v136, v136
	v_add_f32_e32 v253, v237, v135
	v_add_f32_e32 v252, v252, v253
	ds_read_b64_tr_b16 v[186:187], v218
	ds_read_b64_tr_b16 v[188:189], v218 offset:512
	v_mfma_f32_32x32x16_bf16 v[32:47], v[104:107], v[206:209], v[32:47]
	v_exp_f32_e32 v239, v239
	v_exp_f32_e32 v137, v137
	v_add_f32_e32 v253, v238, v136
	v_add_f32_e32 v252, v252, v253
	ds_read_b64_tr_b16 v[190:191], v218 offset:1024
	ds_read_b64_tr_b16 v[192:193], v218 offset:1536
	v_mfma_f32_32x32x16_bf16 v[32:47], v[100:103], v[210:213], v[32:47]
	v_exp_f32_e32 v240, v240
	v_exp_f32_e32 v138, v138
	v_add_f32_e32 v253, v239, v137
	v_add_f32_e32 v252, v252, v253
	ds_read_b64_tr_b16 v[194:195], v218 offset:2048
	ds_read_b64_tr_b16 v[196:197], v218 offset:2560
	v_mfma_f32_32x32x16_bf16 v[32:47], v[96:99], v[214:217], v[32:47]
	v_exp_f32_e32 v241, v241
	v_exp_f32_e32 v139, v139
	v_add_f32_e32 v253, v240, v138
	v_add_f32_e32 v252, v252, v253
	ds_read_b64_tr_b16 v[198:199], v218 offset:3072
	ds_read_b64_tr_b16 v[200:201], v218 offset:3584
	s_and_b64 vcc, exec, s[6:7]
	s_cbranch_vccnz .Lmb1_B_g0mid
	s_add_i32 s45, s37, 1
	s_cmp_ge_u32 s45, s30
	s_cbranch_scc1 .Lmb1_skKBm
	s_add_i32 s45, s44, 0x2000
	s_and_b32 s45, s45, 0x6000
	s_add_i32 s45, s45, s74
	s_mov_b32 s99, m0
	s_mov_b32 m0, s45
	s_nop 0
	global_load_lds_dwordx4 v[114:115], off
	s_mov_b32 m0, s99
	s_mov_b32 s43, 1

; template <bool DO_QK, bool DO_PV> __device__ __forceinline__ void mseg(f32x16& p0, f32x16& p1, f32x16* o, unsigned kaddr, unsigned vaddr, const bf16x8* qr, const f32x16& cin,
;                                                                      bf16x8 pa0, bf16x8 pa1, bf16x8 pa2, bf16x8 pa3) {
;     ...
;     if (DO_QK) {
;         if (DO_PV) asm volatile("s_waitcnt lgkmcnt(8)" : "+v"(kf[0]), "+v"(kf[1]), "+v"(kf[2]), "+v"(kf[3]) :: "memory");
;         else asm volatile("s_waitcnt lgkmcnt(0)" : "+v"(kf[0]), "+v"(kf[1]), "+v"(kf[2]), "+v"(kf[3]) :: "memory");
;         __builtin_amdgcn_sched_barrier(0);
;         p0 = ATT_MFMA(kf[0], qr[0], cin); p1 = ATT_MFMA(kf[1], qr[0], cin);
;         p0 = ATT_MFMA(kf[2], qr[1], p0);  p1 = ATT_MFMA(kf[3], qr[1], p1);
;         __builtin_amdgcn_sched_barrier(0);
;         ATT_RD128(kf[0], kaddr, 4096); ATT_RD128(kf[1], kaddr, 4608); ATT_RD128(kf[2], kaddr, 6144); ATT_RD128(kf[3], kaddr, 6656);
;         asm volatile("s_waitcnt lgkmcnt(0)" : "+v"(kf[0]), "+v"(kf[1]), "+v"(kf[2]), "+v"(kf[3]), "+v"(vl[0]), "+v"(vh[0]), "+v"(vl[1]), "+v"(vh[1]), "+v"(vl[2]), "+v"(vh[2]), "+v"(vl[3]), "+v"(vh[3]) :: "memory");
;         __builtin_amdgcn_sched_barrier(0);
;         p0 = ATT_MFMA(kf[0], qr[2], p0);  p1 = ATT_MFMA(kf[1], qr[2], p1);
;         p0 = ATT_MFMA(kf[2], qr[3], p0);  p1 = ATT_MFMA(kf[3], qr[3], p1);
;         __builtin_amdgcn_sched_barrier(0);
;     }
;     if (DO_PV) {
;         if (!DO_QK) asm volatile("s_waitcnt lgkmcnt(0)" : "+v"(vl[0]), "+v"(vh[0]), "+v"(vl[1]), "+v"(vh[1]), "+v"(vl[2]), "+v"(vh[2]), "+v"(vl[3]), "+v"(vh[3]) :: "memory");
;         __builtin_amdgcn_sched_barrier(0);
;     ...
;         o[0] = ATT_MFMA(pa0, ATT_PK2(vl[0], vh[0]), o[0]); o[0] = ATT_MFMA(pa1, ATT_PK2(vl[1], vh[1]), o[0]);
;         o[0] = ATT_MFMA(pa2, ATT_PK2(vl[2], vh[2]), o[0]); o[0] = ATT_MFMA(pa3, ATT_PK2(vl[3], vh[3]), o[0]);
;         __builtin_amdgcn_sched_barrier(0);
;         ATT_RDTR(vl[0], vaddr, 4096); ATT_RDTR(vh[0], vaddr, 4608); ATT_RDTR(vl[1], vaddr, 5120); ATT_RDTR(vh[1], vaddr, 5632);
;         ATT_RDTR(vl[2], vaddr, 6144); ATT_RDTR(vh[2], vaddr, 6656); ATT_RDTR(vl[3], vaddr, 7168); ATT_RDTR(vh[3], vaddr, 7680);
;         asm volatile("s_waitcnt lgkmcnt(0)" : "+v"(vl[0]), "+v"(vh[0]), "+v"(vl[1]), "+v"(vh[1]), "+v"(vl[2]), "+v"(vh[2]), "+v"(vl[3]), "+v"(vh[3]) :: "memory");
;         __builtin_amdgcn_sched_barrier(0);
.Lmb1_skVBm:
.Lmb1_B_g0mid:
	s_waitcnt lgkmcnt(8)
	v_mfma_f32_32x32x16_bf16 v[64:79], v[154:157], v[92:95], v[220:235]
	v_exp_f32_e32 v242, v242
	v_exp_f32_e32 v140, v140
	v_add_f32_e32 v253, v241, v139
	v_add_f32_e32 v252, v252, v253
	v_cvt_pk_bf16_f32 v108, v236, v237
	v_cvt_pk_bf16_f32 v100, v134, v135
	ds_read_b64_tr_b16 v[202:203], v218 offset:4096
	ds_read_b64_tr_b16 v[204:205], v218 offset:4608
	v_mfma_f32_32x32x16_bf16 v[48:63], v[158:161], v[92:95], v[220:235]
	v_exp_f32_e32 v243, v243
	v_exp_f32_e32 v141, v141
	v_add_f32_e32 v253, v242, v140
	v_add_f32_e32 v252, v252, v253
	v_cvt_pk_bf16_f32 v109, v238, v239
	v_cvt_pk_bf16_f32 v101, v136, v137
	ds_read_b64_tr_b16 v[206:207], v218 offset:5120
	ds_read_b64_tr_b16 v[208:209], v218 offset:5632
	v_mfma_f32_32x32x16_bf16 v[64:79], v[162:165], v[88:91], v[64:79]
	v_exp_f32_e32 v244, v244
	v_exp_f32_e32 v142, v142
	v_add_f32_e32 v253, v243, v141
	v_add_f32_e32 v252, v252, v253
	v_cvt_pk_bf16_f32 v110, v240, v241
	v_cvt_pk_bf16_f32 v102, v138, v139
	ds_read_b64_tr_b16 v[210:211], v218 offset:6144
	ds_read_b64_tr_b16 v[212:213], v218 offset:6656
	v_mfma_f32_32x32x16_bf16 v[48:63], v[166:169], v[88:91], v[48:63]
	v_exp_f32_e32 v245, v245
	v_exp_f32_e32 v143, v143
	v_add_f32_e32 v253, v244, v142
	v_add_f32_e32 v252, v252, v253
	v_cvt_pk_bf16_f32 v111, v242, v243
	v_cvt_pk_bf16_f32 v103, v140, v141
	ds_read_b64_tr_b16 v[214:215], v218 offset:7168
	ds_read_b64_tr_b16 v[216:217], v218 offset:7680
	v_mfma_f32_32x32x16_bf16 v[64:79], v[170:173], v[84:87], v[64:79]
	v_exp_f32_e32 v246, v246
	v_exp_f32_e32 v144, v144
	v_add_f32_e32 v253, v245, v143
	v_add_f32_e32 v252, v252, v253
	v_cvt_pk_bf16_f32 v104, v244, v245
	v_cvt_pk_bf16_f32 v96, v142, v143
	v_mfma_f32_32x32x16_bf16 v[48:63], v[174:177], v[84:87], v[48:63]
	v_exp_f32_e32 v247, v247
	v_exp_f32_e32 v145, v145
	v_add_f32_e32 v253, v246, v144
	v_add_f32_e32 v252, v252, v253
	v_mfma_f32_32x32x16_bf16 v[64:79], v[178:181], v[80:83], v[64:79]
	v_exp_f32_e32 v248, v248
	v_exp_f32_e32 v146, v146
	v_add_f32_e32 v253, v247, v145
	v_add_f32_e32 v252, v252, v253
	v_cvt_pk_bf16_f32 v105, v246, v247
	v_cvt_pk_bf16_f32 v97, v144, v145
	v_mfma_f32_32x32x16_bf16 v[48:63], v[182:185], v[80:83], v[48:63]
	v_exp_f32_e32 v249, v249
	v_exp_f32_e32 v147, v147
	v_add_f32_e32 v253, v248, v146
	v_add_f32_e32 v252, v252, v253
	v_add_f32_e32 v253, v249, v147
	v_add_f32_e32 v252, v252, v253
	v_exp_f32_e32 v250, v250
	v_exp_f32_e32 v148, v148
	v_exp_f32_e32 v251, v251
	v_exp_f32_e32 v149, v149
	s_nop 0
	v_add_f32_e32 v253, v250, v148
	v_add_f32_e32 v252, v252, v253
	v_add_f32_e32 v253, v251, v149
	v_add_f32_e32 v252, v252, v253
	v_cvt_pk_bf16_f32 v106, v248, v249
	v_cvt_pk_bf16_f32 v98, v146, v147
	v_cvt_pk_bf16_f32 v107, v250, v251
	v_cvt_pk_bf16_f32 v99, v148, v149
	v_add_f32_e32 v131, v131, v252

; #define ATT_MFMA(a, b, c) __builtin_amdgcn_mfma_f32_32x32x16_bf16((a), (b), (c), 0, 0, 0)
; #define ATT_RDTR(dst, addr, off) asm volatile("ds_read_b64_tr_b16 %0, %1 offset:%c2" : "=&v"(dst) : "v"(addr), "i"(off) : "memory")
; template <bool DO_QK, bool DO_PV> __device__ __forceinline__ void mseg(f32x16& p0, f32x16& p1, f32x16* o, unsigned kaddr, unsigned vaddr, const bf16x8* qr, const f32x16& cin,
;                                                                      bf16x8 pa0, bf16x8 pa1, bf16x8 pa2, bf16x8 pa3) {
;     ...
;     if (DO_PV) {
;         if (!DO_QK) asm volatile("s_waitcnt lgkmcnt(0)" : "+v"(vl[0]), "+v"(vh[0]), "+v"(vl[1]), "+v"(vh[1]), "+v"(vl[2]), "+v"(vh[2]), "+v"(vl[3]), "+v"(vh[3]) :: "memory");
;         __builtin_amdgcn_sched_barrier(0);
;     ...
;         o[0] = ATT_MFMA(pa0, ATT_PK2(vl[0], vh[0]), o[0]); o[0] = ATT_MFMA(pa1, ATT_PK2(vl[1], vh[1]), o[0]);
;         o[0] = ATT_MFMA(pa2, ATT_PK2(vl[2], vh[2]), o[0]); o[0] = ATT_MFMA(pa3, ATT_PK2(vl[3], vh[3]), o[0]);
;         __builtin_amdgcn_sched_barrier(0);
;         ATT_RDTR(vl[0], vaddr, 4096); ATT_RDTR(vh[0], vaddr, 4608); ATT_RDTR(vl[1], vaddr, 5120); ATT_RDTR(vh[1], vaddr, 5632);
;         ATT_RDTR(vl[2], vaddr, 6144); ATT_RDTR(vh[2], vaddr, 6656); ATT_RDTR(vl[3], vaddr, 7168); ATT_RDTR(vh[3], vaddr, 7680);
;         asm volatile("s_waitcnt lgkmcnt(0)" : "+v"(vl[0]), "+v"(vh[0]), "+v"(vl[1]), "+v"(vh[1]), "+v"(vl[2]), "+v"(vh[2]), "+v"(vl[3]), "+v"(vh[3]) :: "memory");
;         __builtin_amdgcn_sched_barrier(0);
;         o[1] = ATT_MFMA(pa0, ATT_PK2(vl[0], vh[0]), o[1]); o[1] = ATT_MFMA(pa1, ATT_PK2(vl[1], vh[1]), o[1]);
;         o[1] = ATT_MFMA(pa2, ATT_PK2(vl[2], vh[2]), o[1]); o[1] = ATT_MFMA(pa3, ATT_PK2(vl[3], vh[3]), o[1]);
.Lmb3_skVA:
.Lmb3_A_g1top:
	s_add_i32 s36, s43, 0x2000
	s_add_i32 s98, s43, 0x4000
	s_and_b32 s42, s98, 0x6000
	v_add_u32_e32 v133, s42, v130
	ds_read_b128 v[154:157], v133
	ds_read_b128 v[158:161], v133 offset:512
	ds_read_b128 v[162:165], v133 offset:2048
	ds_read_b128 v[166:169], v133 offset:2560
	ds_read_b128 v[170:173], v133 offset:4096
	ds_read_b128 v[174:177], v133 offset:4608
	ds_read_b128 v[178:181], v133 offset:6144
	ds_read_b128 v[182:185], v133 offset:6656
	s_and_b32 s42, s36, 0x6000
	v_add_u32_e32 v218, s42, v132
	s_add_i32 s98, s30, 2
	s_cmp_ge_i32 s30, s29
	s_cbranch_scc1 .Lmb3_A_near
	v_mfma_f32_32x32x16_bf16 v[16:31], v[108:111], v[186:189], v[16:31]
	v_mfma_f32_32x32x16_bf16 v[16:31], v[104:107], v[190:193], v[16:31]
	v_mfma_f32_32x32x16_bf16 v[16:31], v[100:103], v[194:197], v[16:31]
	v_exp_f32_e32 v64, v64
	v_exp_f32_e32 v48, v48
	v_mfma_f32_32x32x16_bf16 v[16:31], v[96:99], v[198:201], v[16:31]
	v_exp_f32_e32 v65, v65
	v_exp_f32_e32 v49, v49
	v_add_f32_e32 v252, v64, v48
	v_mfma_f32_32x32x16_bf16 v[32:47], v[108:111], v[202:205], v[32:47]
	v_exp_f32_e32 v66, v66
	v_exp_f32_e32 v50, v50
	v_add_f32_e32 v253, v65, v49
	v_add_f32_e32 v252, v252, v253
	ds_read_b64_tr_b16 v[186:187], v218
	ds_read_b64_tr_b16 v[188:189], v218 offset:512
	v_mfma_f32_32x32x16_bf16 v[32:47], v[104:107], v[206:209], v[32:47]
	v_exp_f32_e32 v67, v67
	v_exp_f32_e32 v51, v51
	v_add_f32_e32 v253, v66, v50
	v_add_f32_e32 v252, v252, v253
	ds_read_b64_tr_b16 v[190:191], v218 offset:1024
	ds_read_b64_tr_b16 v[192:193], v218 offset:1536
	v_mfma_f32_32x32x16_bf16 v[32:47], v[100:103], v[210:213], v[32:47]
	v_exp_f32_e32 v68, v68
	v_exp_f32_e32 v52, v52
	v_add_f32_e32 v253, v67, v51
	v_add_f32_e32 v252, v252, v253
	ds_read_b64_tr_b16 v[194:195], v218 offset:2048
	ds_read_b64_tr_b16 v[196:197], v218 offset:2560
	v_mfma_f32_32x32x16_bf16 v[32:47], v[96:99], v[214:217], v[32:47]
	v_exp_f32_e32 v69, v69
	v_exp_f32_e32 v53, v53
	v_add_f32_e32 v253, v68, v52
	v_add_f32_e32 v252, v252, v253
	ds_read_b64_tr_b16 v[198:199], v218 offset:3072
	ds_read_b64_tr_b16 v[200:201], v218 offset:3584
	s_and_b64 vcc, exec, s[6:7]
	s_cbranch_vccnz .Lmb3_A_g0mid
	s_add_i32 s42, s35, 1
	s_cmp_ge_u32 s42, s28
	s_cbranch_scc1 .Lmb3_skKAm
	s_add_i32 s42, s43, 0x2000
	s_and_b32 s42, s42, 0x6000
	s_add_i32 s42, s42, s74
	s_mov_b32 s99, m0
	s_mov_b32 m0, s42
	s_nop 0
	global_load_lds_dwordx4 v[114:115], off
	s_mov_b32 m0, s99
	s_mov_b32 s37, 1

; #define ATT_MFMA(a, b, c) __builtin_amdgcn_mfma_f32_32x32x16_bf16((a), (b), (c), 0, 0, 0)
; #define ATT_RDTR(dst, addr, off) asm volatile("ds_read_b64_tr_b16 %0, %1 offset:%c2" : "=&v"(dst) : "v"(addr), "i"(off) : "memory")
; template <bool DO_QK, bool DO_PV> __device__ __forceinline__ void mseg(f32x16& p0, f32x16& p1, f32x16* o, unsigned kaddr, unsigned vaddr, const bf16x8* qr, const f32x16& cin,
;                                                                      bf16x8 pa0, bf16x8 pa1, bf16x8 pa2, bf16x8 pa3) {
;     ...
;     if (DO_PV) {
;         if (!DO_QK) asm volatile("s_waitcnt lgkmcnt(0)" : "+v"(vl[0]), "+v"(vh[0]), "+v"(vl[1]), "+v"(vh[1]), "+v"(vl[2]), "+v"(vh[2]), "+v"(vl[3]), "+v"(vh[3]) :: "memory");
;         __builtin_amdgcn_sched_barrier(0);
;     ...
;         o[0] = ATT_MFMA(pa0, ATT_PK2(vl[0], vh[0]), o[0]); o[0] = ATT_MFMA(pa1, ATT_PK2(vl[1], vh[1]), o[0]);
;         o[0] = ATT_MFMA(pa2, ATT_PK2(vl[2], vh[2]), o[0]); o[0] = ATT_MFMA(pa3, ATT_PK2(vl[3], vh[3]), o[0]);
;         __builtin_amdgcn_sched_barrier(0);
;         ATT_RDTR(vl[0], vaddr, 4096); ATT_RDTR(vh[0], vaddr, 4608); ATT_RDTR(vl[1], vaddr, 5120); ATT_RDTR(vh[1], vaddr, 5632);
;         ATT_RDTR(vl[2], vaddr, 6144); ATT_RDTR(vh[2], vaddr, 6656); ATT_RDTR(vl[3], vaddr, 7168); ATT_RDTR(vh[3], vaddr, 7680);
;         asm volatile("s_waitcnt lgkmcnt(0)" : "+v"(vl[0]), "+v"(vh[0]), "+v"(vl[1]), "+v"(vh[1]), "+v"(vl[2]), "+v"(vh[2]), "+v"(vl[3]), "+v"(vh[3]) :: "memory");
;         __builtin_amdgcn_sched_barrier(0);
;         o[1] = ATT_MFMA(pa0, ATT_PK2(vl[0], vh[0]), o[1]); o[1] = ATT_MFMA(pa1, ATT_PK2(vl[1], vh[1]), o[1]);
;         o[1] = ATT_MFMA(pa2, ATT_PK2(vl[2], vh[2]), o[1]); o[1] = ATT_MFMA(pa3, ATT_PK2(vl[3], vh[3]), o[1]);
.Lmb3_skVB:
.Lmb3_B_g1top:
	s_add_i32 s36, s43, 0x2000
	s_add_i32 s98, s43, 0x4000
	s_and_b32 s42, s98, 0x6000
	v_add_u32_e32 v133, s42, v130
	ds_read_b128 v[154:157], v133
	ds_read_b128 v[158:161], v133 offset:512
	ds_read_b128 v[162:165], v133 offset:2048
	ds_read_b128 v[166:169], v133 offset:2560
	ds_read_b128 v[170:173], v133 offset:4096
	ds_read_b128 v[174:177], v133 offset:4608
	ds_read_b128 v[178:181], v133 offset:6144
	ds_read_b128 v[182:185], v133 offset:6656
	s_and_b32 s42, s36, 0x6000
	v_add_u32_e32 v218, s42, v132
	s_add_i32 s98, s30, 2
	s_cmp_ge_i32 s30, s29
	s_cbranch_scc1 .Lmb3_B_near
	v_mfma_f32_32x32x16_bf16 v[16:31], v[108:111], v[186:189], v[16:31]
	v_mfma_f32_32x32x16_bf16 v[16:31], v[104:107], v[190:193], v[16:31]
	v_mfma_f32_32x32x16_bf16 v[16:31], v[100:103], v[194:197], v[16:31]
	v_exp_f32_e32 v236, v236
	v_exp_f32_e32 v134, v134
	v_mfma_f32_32x32x16_bf16 v[16:31], v[96:99], v[198:201], v[16:31]
	v_exp_f32_e32 v237, v237
	v_exp_f32_e32 v135, v135
	v_add_f32_e32 v252, v236, v134
	v_mfma_f32_32x32x16_bf16 v[32:47], v[108:111], v[202:205], v[32:47]
	v_exp_f32_e32 v238, v238
	v_exp_f32_e32 v136, v136
	v_add_f32_e32 v253, v237, v135
	v_add_f32_e32 v252, v252, v253
	ds_read_b64_tr_b16 v[186:187], v218
	ds_read_b64_tr_b16 v[188:189], v218 offset:512
	v_mfma_f32_32x32x16_bf16 v[32:47], v[104:107], v[206:209], v[32:47]
	v_exp_f32_e32 v239, v239
	v_exp_f32_e32 v137, v137
	v_add_f32_e32 v253, v238, v136
	v_add_f32_e32 v252, v252, v253
	ds_read_b64_tr_b16 v[190:191], v218 offset:1024
	ds_read_b64_tr_b16 v[192:193], v218 offset:1536
	v_mfma_f32_32x32x16_bf16 v[32:47], v[100:103], v[210:213], v[32:47]
	v_exp_f32_e32 v240, v240
	v_exp_f32_e32 v138, v138
	v_add_f32_e32 v253, v239, v137
	v_add_f32_e32 v252, v252, v253
	ds_read_b64_tr_b16 v[194:195], v218 offset:2048
	ds_read_b64_tr_b16 v[196:197], v218 offset:2560
	v_mfma_f32_32x32x16_bf16 v[32:47], v[96:99], v[214:217], v[32:47]
	v_exp_f32_e32 v241, v241
	v_exp_f32_e32 v139, v139
	v_add_f32_e32 v253, v240, v138
	v_add_f32_e32 v252, v252, v253
	ds_read_b64_tr_b16 v[198:199], v218 offset:3072
	ds_read_b64_tr_b16 v[200:201], v218 offset:3584
	s_and_b64 vcc, exec, s[6:7]
	s_cbranch_vccnz .Lmb3_B_g0mid
	s_add_i32 s42, s35, 1
	s_cmp_ge_u32 s42, s28
	s_cbranch_scc1 .Lmb3_skKBm
	s_add_i32 s42, s43, 0x2000
	s_and_b32 s42, s42, 0x6000
	s_add_i32 s42, s42, s74
	s_mov_b32 s99, m0
	s_mov_b32 m0, s42
	s_nop 0
	global_load_lds_dwordx4 v[114:115], off
	s_mov_b32 m0, s99
	s_mov_b32 s37, 1
